# attention key-tile loop: s_setprio 1 from the loop barrier through the last PV MFMA, 0 for the LDS-store tail
# speedup vs baseline: 1.0117x; 1.0040x over previous
; #define MFMA(a, b, c) __builtin_amdgcn_mfma_f32_32x32x16_bf16((a), (b), (c), 0, 0, 0)
; DI void attn_item(const Params& p, const bf16_t* Qbase  , int bh, int q0, int nkeys, int out_row0, unsigned char* smem) {
;     ...
;     for (int ks = 0; ks < 6; ++ks) qf[ks] = ld8(Qbase + (size_t)(q0 + 32 * wave + li) * 96 + 16 * ks + 8 * lh);
;     u32x4 rk[3], rv[2];
;     auto gload = [&](int kt) {
; #pragma unroll
;         for (int i = 0; i < 3; ++i) { int id = tid + 256 * i; rk[i] = *(const u32x4*)(Kg + (size_t)kt * 64 * 96 + id * 8); }
; #pragma unroll
;         for (int i = 0; i < 2; ++i) { int id = tid + 256 * i, v = id >> 3, kc = id & 7; rv[i] = *(const u32x4*)(Vg + (size_t)v * NKEY + kt * 64 + kc * 8); }
;     };
;     auto sstore = [&](int buf) {
; #pragma unroll
;         for (int i = 0; i < 3; ++i) { int id = tid + 256 * i, key = id / 12, dc = id - key * 12; *(u32x4*)(Ks + (buf * 64 + key) * KS + dc * 8) = rk[i]; }
; #pragma unroll
;         for (int i = 0; i < 2; ++i) { int id = tid + 256 * i, v = id >> 3, kc = id & 7; bf16_t* d = Vs + (buf * 64 + v) * VS + kc * 8;
;             u32x2 lo, hi; lo.x = rv[i].x; lo.y = rv[i].y; hi.x = rv[i].z; hi.y = rv[i].w; *(u32x2*)d = lo; *(u32x2*)(d + 4) = hi; }
;     };
;     const int nkt = nkeys >> 6;
;     const float scl = 0.10206207261596577f * 1.4426950408889634f;
;     f32x16 o0 = zero16(), o1 = zero16(); float m = -1e30f, l = 0.f;
;     __syncthreads();
;     gload(0); sstore(0); __syncthreads();
;     for (int kt = 0; kt < nkt; ++kt) {
;         const int buf = kt & 1;
;         if (kt + 1 < nkt) gload(kt + 1);
;         __builtin_amdgcn_sched_barrier(0);
;         f32x16 s0 = zero16(), s1 = zero16();
;         const bf16_t* kb = Ks + (buf * 64 + li) * KS + 8 * lh;
; #pragma unroll
;         for (int ks = 0; ks < 6; ++ks) { s0 = MFMA(ld8(kb + 16 * ks), qf[ks], s0); s1 = MFMA(ld8(kb + 32 * KS + 16 * ks), qf[ks], s1); }
;         float mx = fmaxf(s0[0], s1[0]);
; #pragma unroll
;         for (int r = 1; r < 16; ++r) mx = fmaxf(fmaxf(mx, s0[r]), s1[r]);
;         mx = fmaxf(mx, __shfl_xor(mx, 32));
;         const float mn = fmaxf(m, mx);
;         if (__any(mn > m)) {
;             const float corr = __builtin_amdgcn_exp2f((m - mn) * scl);
;             l *= corr;
; #pragma unroll
;             for (int r = 0; r < 16; ++r) { o0[r] *= corr; o1[r] *= corr; }
;             m = mn;
;         }
.LBB0_414:
	s_setprio 1
	global_load_dwordx4 v[108:111], v122, s[26:27]
	global_load_dwordx4 v[104:107], v124, s[26:27]
	global_load_dwordx4 v[100:103], v126, s[26:27]
	global_load_dwordx4 v[96:99], v118, s[26:27]
	global_load_dwordx4 v[92:95], v120, s[26:27]
	s_and_b32 s9, s8, 64
	s_mul_i32 s12, s9, 0xd0
	s_mul_i32 s13, s9, 0x88
	v_add_u32_e32 v137, s12, v154
	v_add_u32_e32 v148, s13, v155
	v_add_u32_e32 v151, s13, v156
	ds_read_b128 v[202:205], v137
	ds_read_b128 v[206:209], v137 offset:6656
	ds_read_b128 v[210:213], v137 offset:32
	ds_read_b128 v[214:217], v137 offset:6688
	ds_read_b128 v[218:221], v137 offset:64
	s_waitcnt lgkmcnt(4)
	v_mfma_f32_32x32x16_bf16 v[36:51], v[202:205], v[88:91], 0
	ds_read_b128 v[202:205], v137 offset:6720
	s_waitcnt lgkmcnt(4)
	v_mfma_f32_32x32x16_bf16 v[52:67], v[206:209], v[88:91], 0
	ds_read_b128 v[206:209], v137 offset:96
	s_waitcnt lgkmcnt(4)
	v_mfma_f32_32x32x16_bf16 v[36:51], v[210:213], v[84:87], v[36:51]
	ds_read_b128 v[210:213], v137 offset:6752
	s_waitcnt lgkmcnt(4)
	v_mfma_f32_32x32x16_bf16 v[52:67], v[214:217], v[84:87], v[52:67]
	ds_read_b128 v[214:217], v137 offset:128
	s_waitcnt lgkmcnt(4)
	v_mfma_f32_32x32x16_bf16 v[36:51], v[218:221], v[80:83], v[36:51]
	ds_read_b128 v[218:221], v137 offset:6784
	s_waitcnt lgkmcnt(4)
	v_mfma_f32_32x32x16_bf16 v[52:67], v[202:205], v[80:83], v[52:67]
	ds_read_b128 v[202:205], v137 offset:160
	s_waitcnt lgkmcnt(4)
	v_mfma_f32_32x32x16_bf16 v[36:51], v[206:209], v[76:79], v[36:51]
	ds_read_b128 v[206:209], v137 offset:6816
	s_waitcnt lgkmcnt(4)
	v_mfma_f32_32x32x16_bf16 v[52:67], v[210:213], v[76:79], v[52:67]
	ds_read2_b64 v[164:167], v148 offset1:2
	ds_read2_b64 v[176:179], v151 offset0:32 offset1:34
	s_waitcnt lgkmcnt(5)
	v_mfma_f32_32x32x16_bf16 v[36:51], v[214:217], v[72:75], v[36:51]
	ds_read2_b64 v[192:195], v148 offset0:4 offset1:6
	ds_read2_b64 v[196:199], v151 offset0:36 offset1:38
	s_waitcnt lgkmcnt(6)
	v_mfma_f32_32x32x16_bf16 v[52:67], v[218:221], v[72:75], v[52:67]
	ds_read2_b64 v[224:227], v148 offset0:8 offset1:10
	ds_read2_b64 v[228:231], v151 offset0:40 offset1:42
	s_waitcnt lgkmcnt(7)
	v_mfma_f32_32x32x16_bf16 v[36:51], v[202:205], v[68:71], v[36:51]
	ds_read2_b64 v[244:247], v148 offset0:12 offset1:14
	ds_read2_b64 v[248:251], v151 offset0:44 offset1:46
	s_waitcnt lgkmcnt(8)
	v_mfma_f32_32x32x16_bf16 v[52:67], v[206:209], v[68:71], v[52:67]
	s_nop 11
	v_max3_f32 v137, v36, v37, v38
	v_max3_f32 v139, v52, v53, v54
	v_max3_f32 v137, v137, v39, v40
	v_max3_f32 v139, v139, v55, v56
	v_max3_f32 v137, v137, v41, v42
	v_max3_f32 v139, v139, v57, v58
	v_max3_f32 v137, v137, v43, v44
	v_max3_f32 v139, v139, v59, v60
	v_max3_f32 v137, v137, v45, v46
	v_max3_f32 v139, v139, v61, v62
	v_max3_f32 v137, v137, v47, v48
	v_max3_f32 v139, v139, v63, v64
	v_max3_f32 v137, v137, v49, v50
	v_max3_f32 v139, v139, v65, v66
	v_max3_f32 v137, v137, v51, v139
	v_max_f32_e32 v137, v137, v67
	v_mov_b32_e32 v140, v137
	v_mov_b32_e32 v141, v137
	s_nop 1
	v_permlane32_swap_b32_e32 v140, v141
	v_max3_f32 v139, v137, v140, v141
	v_max_f32_e32 v137, v136, v139
	v_cmp_gt_f32_e32 vcc, v137, v136
	s_cbranch_vccz .Lattn_keep
	v_sub_f32_e32 v136, v136, v137
	v_mul_f32_e32 v136, 0x3e16c740, v136
	v_exp_f32_e32 v136, v136
	s_nop 0
	v_pk_mul_f32 v[4:5], v[4:5], v[136:137] op_sel_hi:[1,0]
	v_pk_mul_f32 v[6:7], v[6:7], v[136:137] op_sel_hi:[1,0]
	v_pk_mul_f32 v[8:9], v[8:9], v[136:137] op_sel_hi:[1,0]
	v_pk_mul_f32 v[10:11], v[10:11], v[136:137] op_sel_hi:[1,0]
	v_pk_mul_f32 v[12:13], v[12:13], v[136:137] op_sel_hi:[1,0]
	v_pk_mul_f32 v[14:15], v[14:15], v[136:137] op_sel_hi:[1,0]
	v_pk_mul_f32 v[16:17], v[16:17], v[136:137] op_sel_hi:[1,0]
	v_pk_mul_f32 v[18:19], v[18:19], v[136:137] op_sel_hi:[1,0]
	v_pk_mul_f32 v[20:21], v[20:21], v[136:137] op_sel_hi:[1,0]
	v_pk_mul_f32 v[22:23], v[22:23], v[136:137] op_sel_hi:[1,0]
	v_pk_mul_f32 v[24:25], v[24:25], v[136:137] op_sel_hi:[1,0]
	v_pk_mul_f32 v[26:27], v[26:27], v[136:137] op_sel_hi:[1,0]
	v_pk_mul_f32 v[28:29], v[28:29], v[136:137] op_sel_hi:[1,0]
	v_pk_mul_f32 v[30:31], v[30:31], v[136:137] op_sel_hi:[1,0]
	v_pk_mul_f32 v[32:33], v[32:33], v[136:137] op_sel_hi:[1,0]
	v_pk_mul_f32 v[34:35], v[34:35], v[136:137] op_sel_hi:[1,0]
	v_mul_f32_e32 v0, v0, v136
; #define MFMA(a, b, c) __builtin_amdgcn_mfma_f32_32x32x16_bf16((a), (b), (c), 0, 0, 0)
; DI void attn_item(const Params& p, const bf16_t* Qbase  , int bh, int q0, int nkeys, int out_row0, unsigned char* smem) {
;     ...
;         const float nb = -m * scl;
;         float sum0 = 0.f, sum1 = 0.f;
; #pragma unroll
;         for (int r = 0; r < 16; ++r) { s0[r] = __builtin_amdgcn_exp2f(fmaf(s0[r], scl, nb)); s1[r] = __builtin_amdgcn_exp2f(fmaf(s1[r], scl, nb)); sum0 += s0[r]; sum1 += s1[r]; }
;         float sum = sum0 + sum1;
;         sum += __shfl_xor(sum, 32);
;         l += sum;
;         bf16x8 pf[2][2];
;         pf[0][0] = pack8(s0[0], s0[1], s0[2], s0[3], s0[4], s0[5], s0[6], s0[7]); pf[0][1] = pack8(s0[8], s0[9], s0[10], s0[11], s0[12], s0[13], s0[14], s0[15]);
;         pf[1][0] = pack8(s1[0], s1[1], s1[2], s1[3], s1[4], s1[5], s1[6], s1[7]); pf[1][1] = pack8(s1[8], s1[9], s1[10], s1[11], s1[12], s1[13], s1[14], s1[15]);
;         const bf16_t* vb = Vs + (buf * 64 + li) * VS + 4 * lh;
; #pragma unroll
;         for (int j = 0; j < 2; ++j)
; #pragma unroll
;             for (int s = 0; s < 2; ++s) {
;                 const int ko = 32 * j + 16 * s;
;                 o0 = MFMA(ld4x2(vb + ko, vb + ko + 8), pf[j][s], o0);
;                 o1 = MFMA(ld4x2(vb + 32 * VS + ko, vb + 32 * VS + ko + 8), pf[j][s], o1);
;             }
;         __builtin_amdgcn_sched_barrier(0);
;         if (kt + 1 < nkt) sstore(buf ^ 1);
;         __syncthreads();
.Lattn_keep:
	v_mul_f32_e32 v136, 0xbe16c740, v137
	v_fmamk_f32 v36, v36, 0x3e16c740, v136
	v_fmamk_f32 v37, v37, 0x3e16c740, v136
	v_exp_f32_e32 v36, v36
	v_fmamk_f32 v38, v38, 0x3e16c740, v136
	v_exp_f32_e32 v37, v37
	v_fmamk_f32 v39, v39, 0x3e16c740, v136
	v_exp_f32_e32 v38, v38
	v_fmamk_f32 v40, v40, 0x3e16c740, v136
	v_exp_f32_e32 v39, v39
	v_fmamk_f32 v41, v41, 0x3e16c740, v136
	v_exp_f32_e32 v40, v40
	v_fmamk_f32 v42, v42, 0x3e16c740, v136
	v_exp_f32_e32 v41, v41
	v_fmamk_f32 v43, v43, 0x3e16c740, v136
	v_exp_f32_e32 v42, v42
	v_fmamk_f32 v44, v44, 0x3e16c740, v136
	v_exp_f32_e32 v43, v43
	v_fmamk_f32 v45, v45, 0x3e16c740, v136
	v_exp_f32_e32 v44, v44
	v_fmamk_f32 v46, v46, 0x3e16c740, v136
	v_exp_f32_e32 v45, v45
	v_fmamk_f32 v47, v47, 0x3e16c740, v136
	v_exp_f32_e32 v46, v46
	v_fmamk_f32 v48, v48, 0x3e16c740, v136
	v_exp_f32_e32 v47, v47
	v_fmamk_f32 v49, v49, 0x3e16c740, v136
	v_exp_f32_e32 v48, v48
	v_fmamk_f32 v50, v50, 0x3e16c740, v136
	v_exp_f32_e32 v49, v49
	v_fmamk_f32 v51, v51, 0x3e16c740, v136
	v_exp_f32_e32 v50, v50
	v_fmamk_f32 v52, v52, 0x3e16c740, v136
	v_exp_f32_e32 v51, v51
	v_fmamk_f32 v53, v53, 0x3e16c740, v136
	v_exp_f32_e32 v52, v52
	v_fmamk_f32 v54, v54, 0x3e16c740, v136
	v_exp_f32_e32 v53, v53
	v_fmamk_f32 v55, v55, 0x3e16c740, v136
	v_exp_f32_e32 v54, v54
	v_fmamk_f32 v56, v56, 0x3e16c740, v136
	v_exp_f32_e32 v55, v55
	v_fmamk_f32 v57, v57, 0x3e16c740, v136
	v_exp_f32_e32 v56, v56
	v_fmamk_f32 v58, v58, 0x3e16c740, v136
	v_exp_f32_e32 v57, v57
	v_fmamk_f32 v59, v59, 0x3e16c740, v136
	v_exp_f32_e32 v58, v58
	v_fmamk_f32 v60, v60, 0x3e16c740, v136
	v_exp_f32_e32 v59, v59
	v_fmamk_f32 v61, v61, 0x3e16c740, v136
	v_exp_f32_e32 v60, v60
	v_fmamk_f32 v62, v62, 0x3e16c740, v136
	v_exp_f32_e32 v61, v61
	v_fmamk_f32 v63, v63, 0x3e16c740, v136
	v_exp_f32_e32 v62, v62
	v_fmamk_f32 v64, v64, 0x3e16c740, v136
	v_exp_f32_e32 v63, v63
	v_fmamk_f32 v65, v65, 0x3e16c740, v136
	v_exp_f32_e32 v64, v64
	v_fmamk_f32 v66, v66, 0x3e16c740, v136
	v_exp_f32_e32 v65, v65
	v_fmamk_f32 v67, v67, 0x3e16c740, v136
	v_exp_f32_e32 v66, v66
	v_exp_f32_e32 v67, v67
	v_add_f32_e32 v138, v36, v37
	v_add_f32_e32 v139, v44, v45
	v_add_f32_e32 v152, v52, v53
	v_add_f32_e32 v153, v60, v61
	v_add_f32_e32 v138, v138, v38
	v_add_f32_e32 v139, v139, v46
	v_add_f32_e32 v152, v152, v54
	v_add_f32_e32 v153, v153, v62
	v_add_f32_e32 v138, v138, v39
	v_add_f32_e32 v139, v139, v47
	v_add_f32_e32 v152, v152, v55
	v_add_f32_e32 v153, v153, v63
	v_add_f32_e32 v138, v138, v40
	v_add_f32_e32 v139, v139, v48
	v_add_f32_e32 v152, v152, v56
	v_add_f32_e32 v153, v153, v64
	v_add_f32_e32 v138, v138, v41
	v_add_f32_e32 v139, v139, v49
	v_add_f32_e32 v152, v152, v57
	v_add_f32_e32 v153, v153, v65
	v_add_f32_e32 v138, v138, v42
	v_add_f32_e32 v139, v139, v50
	v_add_f32_e32 v152, v152, v58
	v_add_f32_e32 v153, v153, v66
	v_add_f32_e32 v138, v138, v43
	v_add_f32_e32 v139, v139, v51
	v_add_f32_e32 v152, v152, v59
	v_add_f32_e32 v153, v153, v67
	v_cvt_pk_bf16_f32 v140, v52, v53
	v_cvt_pk_bf16_f32 v141, v54, v55
	v_cvt_pk_bf16_f32 v142, v56, v57
	v_cvt_pk_bf16_f32 v143, v58, v59
	v_cvt_pk_bf16_f32 v144, v60, v61
	v_cvt_pk_bf16_f32 v145, v62, v63
	v_cvt_pk_bf16_f32 v146, v64, v65
	v_cvt_pk_bf16_f32 v147, v66, v67
	v_cvt_pk_bf16_f32 v36, v36, v37
	v_cvt_pk_bf16_f32 v37, v38, v39
	v_cvt_pk_bf16_f32 v38, v40, v41
	v_cvt_pk_bf16_f32 v39, v42, v43
	v_cvt_pk_bf16_f32 v40, v44, v45
	v_cvt_pk_bf16_f32 v41, v46, v47
	v_cvt_pk_bf16_f32 v42, v48, v49
	v_cvt_pk_bf16_f32 v43, v50, v51
	v_add_f32_e32 v138, v138, v139
	v_add_f32_e32 v152, v152, v153
	v_add_f32_e32 v138, v138, v152
	v_add_f32_e32 v0, v0, v138
	s_waitcnt lgkmcnt(0)
	v_mfma_f32_32x32x16_bf16 v[4:19], v[164:167], v[36:39], v[4:19]
	v_mfma_f32_32x32x16_bf16 v[20:35], v[176:179], v[36:39], v[20:35]
	v_mfma_f32_32x32x16_bf16 v[4:19], v[192:195], v[40:43], v[4:19]
	v_mfma_f32_32x32x16_bf16 v[20:35], v[196:199], v[40:43], v[20:35]
	v_mfma_f32_32x32x16_bf16 v[4:19], v[224:227], v[140:143], v[4:19]
	v_mfma_f32_32x32x16_bf16 v[20:35], v[228:231], v[140:143], v[20:35]
	v_mfma_f32_32x32x16_bf16 v[4:19], v[244:247], v[144:147], v[4:19]
	v_mfma_f32_32x32x16_bf16 v[20:35], v[248:251], v[144:147], v[20:35]
	s_setprio 0
	s_xor_b32 s9, s9, 64
	s_mul_i32 s12, s9, 0xd0
	s_mul_i32 s13, s9, 0x88
	v_add_u32_e32 v36, s12, v157
	s_waitcnt vmcnt(4)
	ds_write_b128 v36, v[108:111]
	v_add_u32_e32 v36, s12, v158
	s_waitcnt vmcnt(3)
	ds_write_b128 v36, v[104:107]
	v_add_u32_e32 v36, s12, v159
	s_waitcnt vmcnt(2)
	ds_write_b128 v36, v[100:103]
	v_add_u32_e32 v36, s13, v160
	s_waitcnt vmcnt(1)
	ds_write2_b64 v36, v[96:97], v[98:99] offset1:1
	v_add_u32_e32 v36, s13, v161
	s_add_i32 s8, s8, 64
	v_add_u32_e32 v122, 0x3000, v122
	v_add_u32_e32 v124, 0x3000, v124
	v_add_u32_e32 v126, 0x3000, v126
	v_add_u32_e32 v118, 0x80, v118
	v_add_u32_e32 v120, 0x80, v120
	s_mov_b64 s[10:11], 0x3000
	s_movk_i32 s12, 0x88
	s_movk_i32 s13, 0xd0
	s_movk_i32 s37, 0xd0
	s_movk_i32 s71, 0x88
	s_mov_b64 s[68:69], 0x3000
	s_waitcnt vmcnt(0)
	ds_write2_b64 v36, v[92:93], v[94:95] offset1:1
	s_waitcnt lgkmcnt(0)
	s_barrier
	s_cmpk_eq_i32 s8, 0x10c0
	s_cbranch_scc1 .Lattn_exit
	v_mov_b32_e32 v136, v137
	s_branch .LBB0_414
